# final LayerNorm loop: gain/bias vectors loaded once before the row loop, next row prefetched while the current row is reduced
# speedup vs baseline: 1.0377x; 1.0046x over previous
; #define INP(k) ({ int k_ = (k); asm volatile("" : "+s"(k_)); a.in[k_]; })
; __device__ __forceinline__ void ln_row_f32(float* io, const float* g, const float* b, int lane) {
;     f32x4* xr = (f32x4*)io + lane;
;     f32x4 v[4]; float s = 0.f;
; #pragma unroll
;     for (int j = 0; j < 4; ++j) { v[j] = xr[64 * j]; s += (v[j].x + v[j].y) + (v[j].z + v[j].w); }
;     const float mean = wave_sum(s) * (1.f / D); float s2 = 0.f;
; #pragma unroll
;     for (int j = 0; j < 4; ++j) { v[j] = v[j] - mean; s2 += (v[j].x * v[j].x + v[j].y * v[j].y) + (v[j].z * v[j].z + v[j].w * v[j].w); }
;     const float rstd = rsqrtf(wave_sum(s2) * (1.f / D) + LN_EPS);
; __global__ void __launch_bounds__(NWAVES * 64) mega(Args a) {
;     ...
;             const float* gg = INP(22) + (DEPTH - 1) * D; const float* bb = INP(23) + (DEPTH - 1) * D;
;             for (int m = gw; m < M; m += NGW) ln_row_f32(Y + (size_t)m * D, gg, bb, lane);
.LBB0_745:
	s_and_b64 vcc, exec, s[4:5]
	s_cbranch_vccz .LBB0_749
	v_readlane_b32 s8, v251, 30
	v_readlane_b32 s9, v251, 31
	s_mov_b32 s6, 22
	s_mov_b32 s4, 23
	s_andn2_b64 vcc, exec, s[8:9]
	s_cbranch_vccnz .LBB0_749
	s_waitcnt vmcnt(0)
	v_and_b32_e32 v0, 64, v230
	v_add_u32_e32 v0, 64, v0
	s_waitcnt lgkmcnt(0)
	v_xor_b32_e32 v1, 1, v230
	v_cmp_lt_i32_e32 vcc, v1, v0
	s_ashr_i32 s7, s6, 31
	s_lshl_b64 s[6:7], s[6:7], 3
	v_cndmask_b32_e32 v1, v230, v1, vcc
	v_lshlrev_b32_e32 v37, 2, v1
	v_xor_b32_e32 v1, 2, v230
	v_cmp_lt_i32_e32 vcc, v1, v0
	s_add_u32 s6, s0, s6
	s_addc_u32 s7, s1, s7
	v_cndmask_b32_e32 v1, v230, v1, vcc
	v_lshlrev_b32_e32 v44, 2, v1
	v_xor_b32_e32 v1, 4, v230
	s_ashr_i32 s5, s4, 31
	v_cmp_lt_i32_e32 vcc, v1, v0
	s_lshl_b64 s[4:5], s[4:5], 3
	s_add_u32 s4, s0, s4
	v_cndmask_b32_e32 v1, v230, v1, vcc
	v_lshlrev_b32_e32 v45, 2, v1
	v_xor_b32_e32 v1, 8, v230
	s_addc_u32 s5, s1, s5
	v_cmp_lt_i32_e32 vcc, v1, v0
	s_load_dwordx2 s[4:5], s[4:5], 0x0
	s_nop 0
	s_load_dwordx2 s[6:7], s[6:7], 0x0
	v_cndmask_b32_e32 v1, v230, v1, vcc
	v_lshlrev_b32_e32 v46, 2, v1
	v_xor_b32_e32 v1, 16, v230
	v_cmp_lt_i32_e32 vcc, v1, v0
	s_waitcnt lgkmcnt(0)
	s_add_u32 s4, s4, 0x3000
	s_addc_u32 s5, s5, 0
	v_cndmask_b32_e32 v1, v230, v1, vcc
	v_lshlrev_b32_e32 v47, 2, v1
	v_xor_b32_e32 v1, 32, v230
	v_cmp_lt_i32_e32 vcc, v1, v0
	s_add_u32 s6, s6, 0x3000
	v_lshlrev_b32_e32 v164, 4, v172
	v_cndmask_b32_e32 v0, v230, v1, vcc
	s_addc_u32 s7, s7, 0
	v_lshlrev_b32_e32 v48, 2, v0
	v_or_b32_e32 v0, 0x400, v164
	v_mov_b32_e32 v1, v165
	v_lshl_add_u64 v[20:21], s[6:7], 0, v[0:1]
	v_lshl_add_u64 v[22:23], s[4:5], 0, v[0:1]
	v_or_b32_e32 v0, 0x800, v164
	v_lshl_add_u64 v[24:25], s[6:7], 0, v[0:1]
	v_lshl_add_u64 v[26:27], s[4:5], 0, v[0:1]
	v_or_b32_e32 v0, 0xc00, v164
	v_lshl_add_u64 v[18:19], s[4:5], 0, v[164:165]
	v_lshl_add_u64 v[30:31], s[4:5], 0, v[0:1]
	v_readlane_b32 s4, v253, 33
	v_readlane_b32 s5, v253, 34
	v_lshl_add_u64 v[16:17], s[6:7], 0, v[164:165]
	v_lshl_add_u64 v[28:29], s[6:7], 0, v[0:1]
	v_lshl_add_u64 v[32:33], s[4:5], 0, v[164:165]
	v_readlane_b32 s4, v253, 11
	v_readlane_b32 s5, v253, 12
	global_load_dwordx4 v[180:183], v[16:17], off
	global_load_dwordx4 v[184:187], v[18:19], off
	global_load_dwordx4 v[188:191], v[20:21], off
	global_load_dwordx4 v[192:195], v[22:23], off
	global_load_dwordx4 v[196:199], v[24:25], off
	global_load_dwordx4 v[200:203], v[26:27], off
	global_load_dwordx4 v[204:207], v[28:29], off
	global_load_dwordx4 v[208:211], v[30:31], off
	s_waitcnt vmcnt(0)
	global_load_dwordx4 v[52:55], v[32:33], off offset:-2048
	global_load_dwordx4 v[56:59], v[32:33], off offset:-1024
	global_load_dwordx4 v[60:63], v[32:33], off
	global_load_dwordx4 v[64:67], v[32:33], off offset:1024
	s_waitcnt vmcnt(0)
.LBB0_748:
	s_add_i32 s4, s4, s66
	s_cmpk_gt_i32 s4, 0x7fff
	s_waitcnt vmcnt(4)
	v_mov_b64_e32 v[12:13], v[52:53]
	v_mov_b64_e32 v[14:15], v[54:55]
	v_mov_b64_e32 v[4:5], v[56:57]
	v_mov_b64_e32 v[6:7], v[58:59]
	v_mov_b64_e32 v[8:9], v[60:61]
	v_mov_b64_e32 v[10:11], v[62:63]
	v_mov_b32_e32 v0, v13
	v_mov_b32_e32 v1, v14
	v_mov_b32_e32 v2, v12
	v_mov_b32_e32 v3, v15
	v_pk_add_f32 v[0:1], v[0:1], v[2:3]
	v_mov_b32_e32 v2, v4
	v_add_f32_e32 v0, v0, v1
	v_add_f32_e32 v34, 0, v0
	v_mov_b32_e32 v0, v5
	v_mov_b32_e32 v1, v6
	v_mov_b32_e32 v3, v7
	v_pk_add_f32 v[0:1], v[0:1], v[2:3]
	s_nop 0
	v_pk_add_f32 v[38:39], v[0:1], v[0:1] op_sel:[0,1] op_sel_hi:[1,0]
	v_mov_b64_e32 v[0:1], v[64:65]
	v_mov_b64_e32 v[2:3], v[66:67]
	s_cbranch_scc1 .Lfln_nopf
	v_lshl_add_u64 v[212:213], v[32:33], 0, s[94:95]
	global_load_dwordx4 v[52:55], v[212:213], off offset:-2048
	global_load_dwordx4 v[56:59], v[212:213], off offset:-1024
	global_load_dwordx4 v[60:63], v[212:213], off
	global_load_dwordx4 v[64:67], v[212:213], off offset:1024
; __device__ __forceinline__ void ln_row_f32(float* io, const float* g, const float* b, int lane) {
;     ...
;     for (int j = 0; j < 4; ++j) { v[j] = xr[64 * j]; s += (v[j].x + v[j].y) + (v[j].z + v[j].w); }
;     const float mean = wave_sum(s) * (1.f / D); float s2 = 0.f;
; #pragma unroll
;     for (int j = 0; j < 4; ++j) { v[j] = v[j] - mean; s2 += (v[j].x * v[j].x + v[j].y * v[j].y) + (v[j].z * v[j].z + v[j].w * v[j].w); }
;     const float rstd = rsqrtf(wave_sum(s2) * (1.f / D) + LN_EPS);
; #pragma unroll
;     for (int j = 0; j < 4; ++j) { const int c = (64 * j + lane) * 4; xr[64 * j] = v[j] * rstd * *(const f32x4*)(g + c) + *(const f32x4*)(b + c); }
.Lfln_nopf:
	v_add_f32_e32 v40, v8, v9
	v_add_f32_e32 v42, v10, v11
	v_mov_b32_e32 v35, v0
	v_mov_b32_e32 v39, v1
	v_mov_b32_e32 v41, v2
	v_mov_b32_e32 v43, v3
	v_pk_add_f32 v[34:35], v[34:35], v[38:39]
	v_pk_add_f32 v[38:39], v[40:41], v[42:43]
	s_nop 0
	v_pk_add_f32 v[34:35], v[34:35], v[38:39]
	s_nop 0
	v_add_f32_e32 v34, v34, v35
	ds_bpermute_b32 v35, v37, v34
	s_waitcnt lgkmcnt(0)
	v_add_f32_e32 v34, v34, v35
	ds_bpermute_b32 v35, v44, v34
	s_waitcnt lgkmcnt(0)
	v_add_f32_e32 v34, v34, v35
	ds_bpermute_b32 v35, v45, v34
	s_waitcnt lgkmcnt(0)
	v_add_f32_e32 v34, v34, v35
	ds_bpermute_b32 v35, v46, v34
	s_waitcnt lgkmcnt(0)
	v_add_f32_e32 v34, v34, v35
	ds_bpermute_b32 v35, v47, v34
	s_waitcnt lgkmcnt(0)
	v_add_f32_e32 v34, v34, v35
	ds_bpermute_b32 v35, v48, v34
	s_waitcnt lgkmcnt(0)
	v_add_f32_e32 v36, v34, v35
	v_fmamk_f32 v13, v36, 0xba800000, v13
	v_fmamk_f32 v12, v36, 0xba800000, v12
	v_fmamk_f32 v15, v36, 0xba800000, v15
	v_fmac_f32_e32 v14, 0xba800000, v36
	v_pk_mul_f32 v[34:35], v[14:15], v[14:15]
	v_pk_mul_f32 v[38:39], v[12:13], v[12:13]
	v_fmamk_f32 v7, v36, 0xba800000, v7
	v_pk_mov_b32 v[40:41], v[38:39], v[34:35] op_sel:[1,0]
	v_mov_b32_e32 v39, v35
	v_pk_add_f32 v[34:35], v[40:41], v[38:39]
	v_fmamk_f32 v39, v36, 0xba800000, v5
	v_fmamk_f32 v38, v36, 0xba800000, v4
	v_fmac_f32_e32 v6, 0xba800000, v36
	v_pk_add_f32 v[40:41], v[34:35], v[34:35] op_sel_hi:[0,1]
	v_pk_mul_f32 v[4:5], v[6:7], v[6:7]
	v_pk_mul_f32 v[34:35], v[38:39], v[38:39]
	v_fmac_f32_e32 v10, 0xba800000, v36
	v_pk_mov_b32 v[42:43], v[34:35], v[4:5] op_sel:[1,0]
	v_mov_b32_e32 v35, v5
	v_pk_add_f32 v[4:5], v[42:43], v[34:35]
	v_fmamk_f32 v34, v36, 0xba800000, v8
	v_pk_add_f32 v[4:5], v[4:5], v[4:5] op_sel_hi:[0,1]
	v_fmamk_f32 v35, v36, 0xba800000, v9
	v_mul_f32_e32 v4, v34, v34
	v_fmamk_f32 v11, v36, 0xba800000, v11
	v_pk_fma_f32 v[42:43], v[34:35], v[34:35], v[4:5] op_sel_hi:[1,1,0]
	v_mul_f32_e32 v4, v10, v10
	v_pk_fma_f32 v[50:51], v[10:11], v[10:11], v[4:5] op_sel_hi:[1,1,0]
	v_fmamk_f32 v9, v36, 0xba800000, v3
	v_fmamk_f32 v8, v36, 0xba800000, v2
	v_fmamk_f32 v1, v36, 0xba800000, v1
	v_fmac_f32_e32 v0, 0xba800000, v36
	v_mul_f32_e32 v42, v0, v0
	v_mul_f32_e32 v50, v1, v1
	v_mul_f32_e32 v40, v8, v8
	v_mul_f32_e32 v4, v9, v9
	v_pk_add_f32 v[2:3], v[42:43], v[50:51]
	v_pk_add_f32 v[4:5], v[40:41], v[4:5]
	s_nop 0
	v_pk_add_f32 v[2:3], v[2:3], v[4:5]
	s_nop 0
	v_add_f32_e32 v2, v2, v3
	ds_bpermute_b32 v3, v37, v2
	s_waitcnt lgkmcnt(0)
	v_add_f32_e32 v2, v2, v3
	ds_bpermute_b32 v3, v44, v2
	s_waitcnt lgkmcnt(0)
	v_add_f32_e32 v2, v2, v3
	ds_bpermute_b32 v3, v45, v2
	s_waitcnt lgkmcnt(0)
	v_add_f32_e32 v2, v2, v3
	ds_bpermute_b32 v3, v46, v2
	s_waitcnt lgkmcnt(0)
	v_add_f32_e32 v2, v2, v3
	ds_bpermute_b32 v3, v47, v2
	s_waitcnt lgkmcnt(0)
	v_add_f32_e32 v2, v2, v3
	ds_bpermute_b32 v3, v48, v2
	s_waitcnt lgkmcnt(0)
	v_add_f32_e32 v2, v2, v3
	v_fmamk_f32 v2, v2, 0x3a800000, v173
	v_cmp_gt_f32_e32 vcc, s81, v2
	v_mul_f32_e32 v3, 0x4b800000, v2
	s_nop 0
	v_cndmask_b32_e32 v2, v2, v3, vcc
	v_rsq_f32_e32 v2, v2
	s_nop 0
	v_mul_f32_e32 v3, 0x45800000, v2
	v_cndmask_b32_e32 v36, v2, v3, vcc
	v_pk_mul_f32 v[40:41], v[12:13], v[36:37] op_sel_hi:[1,0]
	v_pk_mul_f32 v[42:43], v[14:15], v[36:37] op_sel_hi:[1,0]
	v_pk_mul_f32 v[6:7], v[6:7], v[36:37] op_sel_hi:[1,0]
	v_pk_mul_f32 v[38:39], v[38:39], v[36:37] op_sel_hi:[1,0]
	v_pk_mul_f32 v[8:9], v[8:9], v[36:37] op_sel_hi:[1,0]
	v_pk_fma_f32 v[4:5], v[182:183], v[42:43], v[186:187]
	v_pk_fma_f32 v[2:3], v[180:181], v[40:41], v[184:185]
	global_store_dwordx4 v[32:33], v[2:5], off offset:-2048
	s_nop 1
	v_pk_fma_f32 v[2:3], v[188:189], v[38:39], v[192:193]
	v_pk_fma_f32 v[4:5], v[190:191], v[6:7], v[194:195]
	global_store_dwordx4 v[32:33], v[2:5], off offset:-1024
	v_pk_mul_f32 v[6:7], v[10:11], v[36:37] op_sel_hi:[1,0]
	v_pk_mul_f32 v[14:15], v[34:35], v[36:37] op_sel_hi:[1,0]
	s_nop 0
	v_pk_fma_f32 v[4:5], v[198:199], v[6:7], v[202:203]
	v_pk_fma_f32 v[2:3], v[196:197], v[14:15], v[200:201]
	global_store_dwordx4 v[32:33], v[2:5], off
	v_pk_mul_f32 v[10:11], v[0:1], v[36:37] op_sel_hi:[1,0]
	s_nop 0
	v_pk_fma_f32 v[0:1], v[204:205], v[10:11], v[208:209]
	v_pk_fma_f32 v[2:3], v[206:207], v[8:9], v[210:211]
	global_store_dwordx4 v[32:33], v[0:3], off offset:1024
	v_lshl_add_u64 v[32:33], v[32:33], 0, s[94:95]
	s_cbranch_scc0 .LBB0_748
